# v5: as v4 but per-tile LDS-DMA issue moved into PV phase (one load per k-step)
# baseline (speedup 1.0000x reference)
; #define MFMA32(a, b, c) __builtin_amdgcn_mfma_f32_32x32x16_bf16((a), (b), (c), 0, 0, 0)
; #define SBAR() __builtin_amdgcn_sched_barrier(0)
; template <int D0> __device__ __forceinline__ void pv_one(f32x16& od, int vb, bf16x8 pa0, bf16x8 pa1, bf16x8 pa2, bf16x8 pa3) {
;     const s16x4 l0 = tr_read<v_rd_off(D0, 0, 0)>(vb), h0 = tr_read<v_rd_off(D0, 0, 1)>(vb), l1 = tr_read<v_rd_off(D0, 1, 0)>(vb), h1 = tr_read<v_rd_off(D0, 1, 1)>(vb);
;     const s16x4 l2 = tr_read<v_rd_off(D0, 2, 0)>(vb), h2 = tr_read<v_rd_off(D0, 2, 1)>(vb), l3 = tr_read<v_rd_off(D0, 3, 0)>(vb), h3 = tr_read<v_rd_off(D0, 3, 1)>(vb);
;     asm volatile("s_waitcnt lgkmcnt(0)" ::: "memory"); SBAR();
;     ...
;     od = MFMA32(pa0, PK(l0, h0), od); od = MFMA32(pa1, PK(l1, h1), od); od = MFMA32(pa2, PK(l2, h2), od); od = MFMA32(pa3, PK(l3, h3), od);
;     ...
; }
; __device__ __forceinline__ void pv_d0(f32x16* o, int vb, bf16x8 pa0, bf16x8 pa1, bf16x8 pa2, bf16x8 pa3) {
;     pv_one<0>(o[0], vb, pa0, pa1, pa2, pa3); pv_one<1>(o[1], vb, pa0, pa1, pa2, pa3); pv_one<2>(o[2], vb, pa0, pa1, pa2, pa3); pv_one<3>(o[3], vb, pa0, pa1, pa2, pa3);
; template <bool FIXED>
; __device__ __forceinline__ float softmax_tile(f32x16& p0, f32x16& p1, float& m_reg, float& l_reg, bf16x8& pa0, bf16x8& pa1, bf16x8& pa2, bf16x8& pa3) {
;     ...
; #pragma unroll
;         for (int r = 0; r < 16; ++r) { p0[r] = __builtin_amdgcn_exp2f(p0[r]); p1[r] = __builtin_amdgcn_exp2f(p1[r]); }
;     }
;     float ps = 0.f;
; #pragma unroll
;     for (int r = 0; r < 16; ++r) ps += p0[r];
; #pragma unroll
;     for (int r = 0; r < 16; ++r) ps += p1[r];
;     ps = half_sum(ps);
;     l_reg = l_reg * alpha + ps;
;     ...
;     PK4(p0, 0, pa0); PK4(p0, 8, pa1); PK4(p1, 0, pa2); PK4(p1, 8, pa3);
.Lattn_exp2:
	v_add_u32_e32 v5, s29, v200
	ds_read_b64_tr_b16 v[228:229], v5 offset:0
	ds_read_b64_tr_b16 v[230:231], v5 offset:2048
	ds_read_b64_tr_b16 v[240:241], v5 offset:512
	ds_read_b64_tr_b16 v[242:243], v5 offset:2560
	ds_read_b64_tr_b16 v[244:245], v5 offset:1024
	ds_read_b64_tr_b16 v[246:247], v5 offset:3072
	s_nop 2
	v_exp_f32_e32 v70, v70
	v_exp_f32_e32 v71, v71
	v_add_f32_e32 v2, 0, v70
	v_exp_f32_e32 v72, v72
	v_add_f32_e32 v2, v71, v2
	v_exp_f32_e32 v73, v73
	v_add_f32_e32 v2, v72, v2
	v_exp_f32_e32 v74, v74
	v_add_f32_e32 v2, v73, v2
	v_exp_f32_e32 v75, v75
	v_add_f32_e32 v2, v74, v2
	v_exp_f32_e32 v76, v76
	v_add_f32_e32 v2, v75, v2
	v_exp_f32_e32 v77, v77
	v_add_f32_e32 v2, v76, v2
	v_cvt_pk_bf16_f32 v70, v70, v71
	v_add_f32_e32 v2, v77, v2
	v_cvt_pk_bf16_f32 v71, v72, v73
	v_cvt_pk_bf16_f32 v72, v74, v75
	v_cvt_pk_bf16_f32 v73, v76, v77
	ds_read_b64_tr_b16 v[74:75], v5 offset:1536
	ds_read_b64_tr_b16 v[76:77], v5 offset:3584
	v_permlane32_swap_b32_e32 v70, v72
	v_permlane32_swap_b32_e32 v71, v73
	s_waitcnt lgkmcnt(6)
	s_nop 0
	v_mfma_f32_32x32x16_bf16 v[54:69], v[70:73], v[228:231], v[54:69]
	ds_read_b64_tr_b16 v[228:229], v5 offset:4096
	ds_read_b64_tr_b16 v[230:231], v5 offset:6144
	v_exp_f32_e32 v78, v78
	v_exp_f32_e32 v79, v79
	v_add_f32_e32 v2, v78, v2
	v_exp_f32_e32 v80, v80
	v_add_f32_e32 v2, v79, v2
	v_exp_f32_e32 v81, v81
	s_waitcnt lgkmcnt(6)
	v_mfma_f32_32x32x16_bf16 v[38:53], v[70:73], v[240:243], v[38:53]
	ds_read_b64_tr_b16 v[240:241], v5 offset:4608
	ds_read_b64_tr_b16 v[242:243], v5 offset:6656
	v_add_f32_e32 v2, v80, v2
	v_exp_f32_e32 v82, v82
	v_add_f32_e32 v2, v81, v2
	v_exp_f32_e32 v83, v83
	v_add_f32_e32 v2, v82, v2
	v_exp_f32_e32 v84, v84
	s_waitcnt lgkmcnt(6)
	v_mfma_f32_32x32x16_bf16 v[22:37], v[70:73], v[244:247], v[22:37]
	ds_read_b64_tr_b16 v[244:245], v5 offset:5120
	ds_read_b64_tr_b16 v[246:247], v5 offset:7168
	v_add_f32_e32 v2, v83, v2
	v_exp_f32_e32 v85, v85
	v_add_f32_e32 v2, v84, v2
	v_cvt_pk_bf16_f32 v78, v78, v79
	v_add_f32_e32 v2, v85, v2
	s_waitcnt lgkmcnt(6)
	v_mfma_f32_32x32x16_bf16 v[6:21], v[70:73], v[74:77], v[6:21]
	v_cvt_pk_bf16_f32 v79, v80, v81
	v_cvt_pk_bf16_f32 v80, v82, v83
	v_cvt_pk_bf16_f32 v81, v84, v85
	ds_read_b64_tr_b16 v[74:75], v5 offset:5632
	ds_read_b64_tr_b16 v[76:77], v5 offset:7680
	v_permlane32_swap_b32_e32 v78, v80
	v_permlane32_swap_b32_e32 v79, v81
	s_waitcnt lgkmcnt(6)
	s_nop 0
	v_mfma_f32_32x32x16_bf16 v[54:69], v[78:81], v[228:231], v[54:69]
	ds_read_b64_tr_b16 v[228:229], v5 offset:8192
	ds_read_b64_tr_b16 v[230:231], v5 offset:10240
	v_exp_f32_e32 v86, v86
	v_exp_f32_e32 v87, v87
	v_add_f32_e32 v2, v86, v2
	v_exp_f32_e32 v88, v88
	v_add_f32_e32 v2, v87, v2
	v_exp_f32_e32 v89, v89
	s_waitcnt lgkmcnt(6)
	v_mfma_f32_32x32x16_bf16 v[38:53], v[78:81], v[240:243], v[38:53]
	s_min_i32 s3, s100, s101
	s_mul_i32 s98, s3, 0x218000
	s_add_i32 s32, s53, s73
	s_mov_b32 m0, s32
	v_lshl_add_u64 v[106:107], v[102:103], 0, s[98:99]
	v_lshl_add_u64 v[108:109], v[104:105], 0, s[98:99]
	global_load_lds_dwordx4 v[106:107], off
	ds_read_b64_tr_b16 v[240:241], v5 offset:8704
	ds_read_b64_tr_b16 v[242:243], v5 offset:10752
	v_add_f32_e32 v2, v88, v2
	v_exp_f32_e32 v90, v90
	v_add_f32_e32 v2, v89, v2
	v_exp_f32_e32 v91, v91
	v_add_f32_e32 v2, v90, v2
	v_exp_f32_e32 v92, v92
	s_waitcnt lgkmcnt(6)
	v_mfma_f32_32x32x16_bf16 v[22:37], v[78:81], v[244:247], v[22:37]
	ds_read_b64_tr_b16 v[244:245], v5 offset:9216
	ds_read_b64_tr_b16 v[246:247], v5 offset:11264
	v_add_f32_e32 v2, v91, v2
	v_exp_f32_e32 v93, v93
	v_add_f32_e32 v2, v92, v2
	v_cvt_pk_bf16_f32 v86, v86, v87
	v_add_f32_e32 v2, v93, v2
	s_waitcnt lgkmcnt(6)
	v_mfma_f32_32x32x16_bf16 v[6:21], v[78:81], v[74:77], v[6:21]
	v_cvt_pk_bf16_f32 v87, v88, v89
	v_cvt_pk_bf16_f32 v88, v90, v91
	v_cvt_pk_bf16_f32 v89, v92, v93
	ds_read_b64_tr_b16 v[74:75], v5 offset:9728
	ds_read_b64_tr_b16 v[76:77], v5 offset:11776
	v_permlane32_swap_b32_e32 v86, v88
	v_permlane32_swap_b32_e32 v87, v89
	s_waitcnt lgkmcnt(6)
	s_nop 0
	v_mfma_f32_32x32x16_bf16 v[54:69], v[86:89], v[228:231], v[54:69]
	ds_read_b64_tr_b16 v[228:229], v5 offset:12288
	ds_read_b64_tr_b16 v[230:231], v5 offset:14336
	v_exp_f32_e32 v94, v94
	v_exp_f32_e32 v95, v95
	v_add_f32_e32 v2, v94, v2
	v_exp_f32_e32 v96, v96
	v_add_f32_e32 v2, v95, v2
	v_exp_f32_e32 v97, v97
	s_waitcnt lgkmcnt(6)
	v_mfma_f32_32x32x16_bf16 v[38:53], v[86:89], v[240:243], v[38:53]
	s_add_i32 m0, s32, 0x380
	s_lshr_b32 s3, s73, 1
	s_add_i32 s3, s3, s53
	global_load_lds_dwordx4 v[106:107], off offset:128
	ds_read_b64_tr_b16 v[240:241], v5 offset:12800
	ds_read_b64_tr_b16 v[242:243], v5 offset:14848
	v_add_f32_e32 v2, v96, v2
	v_exp_f32_e32 v98, v98
	v_add_f32_e32 v2, v97, v2
	v_exp_f32_e32 v99, v99
	v_add_f32_e32 v2, v98, v2
	v_exp_f32_e32 v100, v100
	s_waitcnt lgkmcnt(6)
	v_mfma_f32_32x32x16_bf16 v[22:37], v[86:89], v[244:247], v[22:37]
	ds_read_b64_tr_b16 v[244:245], v5 offset:13312
	ds_read_b64_tr_b16 v[246:247], v5 offset:15360
	v_add_f32_e32 v2, v99, v2
	v_exp_f32_e32 v101, v101
	v_add_f32_e32 v2, v100, v2
	v_cvt_pk_bf16_f32 v94, v94, v95
	v_add_f32_e32 v2, v101, v2
	s_waitcnt lgkmcnt(6)
	v_mfma_f32_32x32x16_bf16 v[6:21], v[86:89], v[74:77], v[6:21]
	v_cvt_pk_bf16_f32 v95, v96, v97
	v_cvt_pk_bf16_f32 v96, v98, v99
	v_cvt_pk_bf16_f32 v97, v100, v101
	ds_read_b64_tr_b16 v[74:75], v5 offset:13824
	ds_read_b64_tr_b16 v[76:77], v5 offset:15872
	v_permlane32_swap_b32_e32 v94, v96
	v_permlane32_swap_b32_e32 v95, v97
	v_mov_b32_e32 v3, v2
	s_waitcnt lgkmcnt(6)
	s_nop 0
	v_mfma_f32_32x32x16_bf16 v[54:69], v[94:97], v[228:231], v[54:69]
	v_mov_b32_e32 v236, v238
	s_waitcnt lgkmcnt(4)
	v_mfma_f32_32x32x16_bf16 v[38:53], v[94:97], v[240:243], v[38:53]
	s_add_i32 m0, s3, 0x10000
	s_add_i32 s100, s100, 1
	s_add_i32 s53, s53, 0x4000
	global_load_lds_dwordx4 v[108:109], off
	s_and_b32 s53, s53, 0xc000
	v_permlane32_swap_b32_e32 v2, v3
	s_waitcnt lgkmcnt(2)
	v_mfma_f32_32x32x16_bf16 v[22:37], v[94:97], v[244:247], v[22:37]
	s_waitcnt lgkmcnt(0)
	v_mfma_f32_32x32x16_bf16 v[6:21], v[94:97], v[74:77], v[6:21]
	v_add_f32_e32 v2, v2, v3
	v_add_f32_e32 v219, v219, v2

.LBB0_937:
	s_add_i32 s10, s60, 0xffffc000
	s_and_b32 s29, s10, 0xc000
	s_add_i32 s14, s29, 0x8000
	v_add_u32_e32 v2, 1, v236
	v_cmp_ge_i32_e32 vcc, v2, v188
	v_add_u32_e32 v237, 64, v235
	v_add_u32_e32 v2, s14, v207
	s_waitcnt vmcnt(6)
	s_waitcnt lgkmcnt(0)
	s_barrier
	v_add_u32_e32 v3, v2, v167
	ds_read_b128 v[70:73], v3 offset:32768
	v_add_u32_e32 v3, v2, v212
	ds_read_b128 v[90:93], v3 offset:32768
	v_add_u32_e32 v3, v2, v214
	ds_read_b128 v[94:97], v3 offset:32768
	v_add_u32_e32 v3, v2, v216
	ds_read_b128 v[98:101], v3 offset:32768
	v_add_u32_e32 v3, s14, v211
	ds_read_b128 v[86:89], v3 offset:32768
	v_add_u32_e32 v3, s14, v213
	ds_read_b128 v[228:231], v3 offset:32768
	v_add_u32_e32 v3, s14, v215
	ds_read_b128 v[240:243], v3 offset:32768
	v_add_u32_e32 v3, s14, v217
	ds_read_b128 v[244:247], v3 offset:32768
	v_add_u32_e32 v3, 63, v235
	v_cmp_le_i32_e64 s[12:13], s27, v3
	v_cmp_gt_i32_e64 s[10:11], s27, v3
	v_cmp_ge_i32_e64 s[14:15], s18, v235
	v_cvt_f32_i32_e32 v2, v235
	s_and_b64 s[12:13], s[12:13], s[14:15]
	s_cmp_eq_u64 s[12:13], 0
	s_cbranch_scc0 .Lattn_nl1
	s_waitcnt lgkmcnt(7)
	v_mfma_f32_32x32x16_bf16 v[70:85], v[70:73], v[114:117], 0
	v_cndmask_b32_e64 v3, -v189, v189, s[10:11]
	v_sub_f32_e32 v2, v191, v2
	v_mul_f32_e64 v2, v2, -v3
	v_cvt_pk_bf16_f32 v5, v2, v3
	v_lshlrev_b32_e32 v196, 16, v5
	v_and_b32_e32 v197, 0xffff0000, v5
	s_waitcnt lgkmcnt(6)
	v_mfma_f32_32x32x16_bf16 v[70:85], v[90:93], v[118:121], v[70:85]
	v_pk_add_f32 v[2:3], v[2:3], v[196:197] neg_lo:[0,1] neg_hi:[0,1]
	s_nop 0
	v_cvt_pk_bf16_f32 v2, v2, v3
	v_and_b32_e32 v3, 0xffff, v5
	v_lshl_or_b32 v183, v2, 16, v3
	s_waitcnt lgkmcnt(5)
	v_mfma_f32_32x32x16_bf16 v[70:85], v[94:97], v[122:125], v[70:85]
	v_lshrrev_b32_e32 v3, 16, v5
	v_and_or_b32 v2, v2, s28, v3
	v_cndmask_b32_e64 v3, 0, v2, s[4:5]
	v_cndmask_b32_e64 v2, 0, v183, s[4:5]
	v_mov_b32_e32 v5, v4
	s_waitcnt lgkmcnt(4)
	v_mfma_f32_32x32x16_bf16 v[70:85], v[98:101], v[126:129], v[70:85]
	s_waitcnt lgkmcnt(3)
	v_mfma_f32_32x32x16_bf16 v[86:101], v[86:89], v[114:117], 0
	s_waitcnt lgkmcnt(2)
	v_mfma_f32_32x32x16_bf16 v[86:101], v[228:231], v[118:121], v[86:101]
	s_waitcnt lgkmcnt(1)
	v_mfma_f32_32x32x16_bf16 v[86:101], v[240:243], v[122:125], v[86:101]
	s_waitcnt lgkmcnt(0)
	v_mfma_f32_32x32x16_bf16 v[86:101], v[244:247], v[126:129], v[86:101]
	v_mfma_f32_32x32x16_bf16 v[70:85], v[110:113], v[2:5], v[70:85]
	v_mfma_f32_32x32x16_bf16 v[86:101], v[176:179], v[2:5], v[86:101]
	s_branch .Lattn_exp1

; #define MFMA32(a, b, c) __builtin_amdgcn_mfma_f32_32x32x16_bf16((a), (b), (c), 0, 0, 0)
; #define SBAR() __builtin_amdgcn_sched_barrier(0)
; template <int D0> __device__ __forceinline__ void pv_one(f32x16& od, int vb, bf16x8 pa0, bf16x8 pa1, bf16x8 pa2, bf16x8 pa3) {
;     const s16x4 l0 = tr_read<v_rd_off(D0, 0, 0)>(vb), h0 = tr_read<v_rd_off(D0, 0, 1)>(vb), l1 = tr_read<v_rd_off(D0, 1, 0)>(vb), h1 = tr_read<v_rd_off(D0, 1, 1)>(vb);
;     const s16x4 l2 = tr_read<v_rd_off(D0, 2, 0)>(vb), h2 = tr_read<v_rd_off(D0, 2, 1)>(vb), l3 = tr_read<v_rd_off(D0, 3, 0)>(vb), h3 = tr_read<v_rd_off(D0, 3, 1)>(vb);
;     asm volatile("s_waitcnt lgkmcnt(0)" ::: "memory"); SBAR();
;     ...
;     od = MFMA32(pa0, PK(l0, h0), od); od = MFMA32(pa1, PK(l1, h1), od); od = MFMA32(pa2, PK(l2, h2), od); od = MFMA32(pa3, PK(l3, h3), od);
;     ...
; }
; __device__ __forceinline__ void pv_d0(f32x16* o, int vb, bf16x8 pa0, bf16x8 pa1, bf16x8 pa2, bf16x8 pa3) {
;     pv_one<0>(o[0], vb, pa0, pa1, pa2, pa3); pv_one<1>(o[1], vb, pa0, pa1, pa2, pa3); pv_one<2>(o[2], vb, pa0, pa1, pa2, pa3); pv_one<3>(o[3], vb, pa0, pa1, pa2, pa3);
; template <bool FIXED>
; __device__ __forceinline__ float softmax_tile(f32x16& p0, f32x16& p1, float& m_reg, float& l_reg, bf16x8& pa0, bf16x8& pa1, bf16x8& pa2, bf16x8& pa3) {
;     ...
; #pragma unroll
;         for (int r = 0; r < 16; ++r) { p0[r] = __builtin_amdgcn_exp2f(p0[r]); p1[r] = __builtin_amdgcn_exp2f(p1[r]); }
;     }
;     float ps = 0.f;
; #pragma unroll
;     for (int r = 0; r < 16; ++r) ps += p0[r];
; #pragma unroll
;     for (int r = 0; r < 16; ++r) ps += p1[r];
;     ps = half_sum(ps);
;     l_reg = l_reg * alpha + ps;
;     ...
;     PK4(p0, 0, pa0); PK4(p0, 8, pa1); PK4(p1, 0, pa2); PK4(p1, 8, pa3);
; template <int MODE, bool FIXED>
; __device__ __forceinline__ void attn_unit(LAS unsigned char* lds, unsigned char* ws, const AttnParams& P, int l, int Tp, int sq, int h, int qb, int part, int np, int pslot, int tid, int wave, int lane) {
;     ...
;         for (int j = jlo; j < jhi; j += 2) {
;             TILE(sA, j);
;             if (j + 1 < jhi) { if (DEPTH == 2) TILE(sB, j + 1); else TILE(sA, j + 1); }
.Lattn_exp1:
	v_add_u32_e32 v5, s29, v200
	ds_read_b64_tr_b16 v[228:229], v5 offset:0
	ds_read_b64_tr_b16 v[230:231], v5 offset:2048
	ds_read_b64_tr_b16 v[240:241], v5 offset:512
	ds_read_b64_tr_b16 v[242:243], v5 offset:2560
	ds_read_b64_tr_b16 v[244:245], v5 offset:1024
	ds_read_b64_tr_b16 v[246:247], v5 offset:3072
	s_nop 2
	v_exp_f32_e32 v70, v70
	v_exp_f32_e32 v71, v71
	v_add_f32_e32 v2, 0, v70
	v_exp_f32_e32 v72, v72
	v_add_f32_e32 v2, v71, v2
	v_exp_f32_e32 v73, v73
	v_add_f32_e32 v2, v72, v2
	v_exp_f32_e32 v74, v74
	v_add_f32_e32 v2, v73, v2
	v_exp_f32_e32 v75, v75
	v_add_f32_e32 v2, v74, v2
	v_exp_f32_e32 v76, v76
	v_add_f32_e32 v2, v75, v2
	v_exp_f32_e32 v77, v77
	v_add_f32_e32 v2, v76, v2
	v_cvt_pk_bf16_f32 v70, v70, v71
	v_add_f32_e32 v2, v77, v2
	v_cvt_pk_bf16_f32 v71, v72, v73
	v_cvt_pk_bf16_f32 v72, v74, v75
	v_cvt_pk_bf16_f32 v73, v76, v77
	ds_read_b64_tr_b16 v[74:75], v5 offset:1536
	ds_read_b64_tr_b16 v[76:77], v5 offset:3584
	v_permlane32_swap_b32_e32 v70, v72
	v_permlane32_swap_b32_e32 v71, v73
	s_waitcnt lgkmcnt(6)
	s_nop 0
	v_mfma_f32_32x32x16_bf16 v[54:69], v[70:73], v[228:231], v[54:69]
	ds_read_b64_tr_b16 v[228:229], v5 offset:4096
	ds_read_b64_tr_b16 v[230:231], v5 offset:6144
	v_exp_f32_e32 v78, v78
	v_exp_f32_e32 v79, v79
	v_add_f32_e32 v2, v78, v2
	v_exp_f32_e32 v80, v80
	v_add_f32_e32 v2, v79, v2
	v_exp_f32_e32 v81, v81
	s_waitcnt lgkmcnt(6)
	v_mfma_f32_32x32x16_bf16 v[38:53], v[70:73], v[240:243], v[38:53]
	ds_read_b64_tr_b16 v[240:241], v5 offset:4608
	ds_read_b64_tr_b16 v[242:243], v5 offset:6656
	v_add_f32_e32 v2, v80, v2
	v_exp_f32_e32 v82, v82
	v_add_f32_e32 v2, v81, v2
	v_exp_f32_e32 v83, v83
	v_add_f32_e32 v2, v82, v2
	v_exp_f32_e32 v84, v84
	s_waitcnt lgkmcnt(6)
	v_mfma_f32_32x32x16_bf16 v[22:37], v[70:73], v[244:247], v[22:37]
	ds_read_b64_tr_b16 v[244:245], v5 offset:5120
	ds_read_b64_tr_b16 v[246:247], v5 offset:7168
	v_add_f32_e32 v2, v83, v2
	v_exp_f32_e32 v85, v85
	v_add_f32_e32 v2, v84, v2
	v_cvt_pk_bf16_f32 v78, v78, v79
	v_add_f32_e32 v2, v85, v2
	s_waitcnt lgkmcnt(6)
	v_mfma_f32_32x32x16_bf16 v[6:21], v[70:73], v[74:77], v[6:21]
	v_cvt_pk_bf16_f32 v79, v80, v81
	v_cvt_pk_bf16_f32 v80, v82, v83
	v_cvt_pk_bf16_f32 v81, v84, v85
	ds_read_b64_tr_b16 v[74:75], v5 offset:5632
	ds_read_b64_tr_b16 v[76:77], v5 offset:7680
	v_permlane32_swap_b32_e32 v78, v80
	v_permlane32_swap_b32_e32 v79, v81
	s_waitcnt lgkmcnt(6)
	s_nop 0
	v_mfma_f32_32x32x16_bf16 v[54:69], v[78:81], v[228:231], v[54:69]
	ds_read_b64_tr_b16 v[228:229], v5 offset:8192
	ds_read_b64_tr_b16 v[230:231], v5 offset:10240
	v_exp_f32_e32 v86, v86
	v_exp_f32_e32 v87, v87
	v_add_f32_e32 v2, v86, v2
	v_exp_f32_e32 v88, v88
	v_add_f32_e32 v2, v87, v2
	v_exp_f32_e32 v89, v89
	s_waitcnt lgkmcnt(6)
	v_mfma_f32_32x32x16_bf16 v[38:53], v[78:81], v[240:243], v[38:53]
	s_min_i32 s3, s100, s101
	s_mul_i32 s98, s3, 0x218000
	s_add_i32 s32, s53, s73
	s_mov_b32 m0, s32
	v_lshl_add_u64 v[106:107], v[102:103], 0, s[98:99]
	v_lshl_add_u64 v[108:109], v[104:105], 0, s[98:99]
	global_load_lds_dwordx4 v[106:107], off
	ds_read_b64_tr_b16 v[240:241], v5 offset:8704
	ds_read_b64_tr_b16 v[242:243], v5 offset:10752
	v_add_f32_e32 v2, v88, v2
	v_exp_f32_e32 v90, v90
	v_add_f32_e32 v2, v89, v2
	v_exp_f32_e32 v91, v91
	v_add_f32_e32 v2, v90, v2
	v_exp_f32_e32 v92, v92
	s_waitcnt lgkmcnt(6)
	v_mfma_f32_32x32x16_bf16 v[22:37], v[78:81], v[244:247], v[22:37]
	ds_read_b64_tr_b16 v[244:245], v5 offset:9216
	ds_read_b64_tr_b16 v[246:247], v5 offset:11264
	v_add_f32_e32 v2, v91, v2
	v_exp_f32_e32 v93, v93
	v_add_f32_e32 v2, v92, v2
	v_cvt_pk_bf16_f32 v86, v86, v87
	v_add_f32_e32 v2, v93, v2
	s_waitcnt lgkmcnt(6)
	v_mfma_f32_32x32x16_bf16 v[6:21], v[78:81], v[74:77], v[6:21]
	v_cvt_pk_bf16_f32 v87, v88, v89
	v_cvt_pk_bf16_f32 v88, v90, v91
	v_cvt_pk_bf16_f32 v89, v92, v93
	ds_read_b64_tr_b16 v[74:75], v5 offset:9728
	ds_read_b64_tr_b16 v[76:77], v5 offset:11776
	v_permlane32_swap_b32_e32 v86, v88
	v_permlane32_swap_b32_e32 v87, v89
	s_waitcnt lgkmcnt(6)
	s_nop 0
	v_mfma_f32_32x32x16_bf16 v[54:69], v[86:89], v[228:231], v[54:69]
	ds_read_b64_tr_b16 v[228:229], v5 offset:12288
	ds_read_b64_tr_b16 v[230:231], v5 offset:14336
	v_exp_f32_e32 v94, v94
	v_exp_f32_e32 v95, v95
	v_add_f32_e32 v2, v94, v2
	v_exp_f32_e32 v96, v96
	v_add_f32_e32 v2, v95, v2
	v_exp_f32_e32 v97, v97
	s_waitcnt lgkmcnt(6)
	v_mfma_f32_32x32x16_bf16 v[38:53], v[86:89], v[240:243], v[38:53]
	s_add_i32 m0, s32, 0x380
	s_lshr_b32 s3, s73, 1
	s_add_i32 s3, s3, s53
	global_load_lds_dwordx4 v[106:107], off offset:128
	ds_read_b64_tr_b16 v[240:241], v5 offset:12800
	ds_read_b64_tr_b16 v[242:243], v5 offset:14848
	v_add_f32_e32 v2, v96, v2
	v_exp_f32_e32 v98, v98
	v_add_f32_e32 v2, v97, v2
	v_exp_f32_e32 v99, v99
	v_add_f32_e32 v2, v98, v2
	v_exp_f32_e32 v100, v100
	s_waitcnt lgkmcnt(6)
	v_mfma_f32_32x32x16_bf16 v[22:37], v[86:89], v[244:247], v[22:37]
	ds_read_b64_tr_b16 v[244:245], v5 offset:13312
	ds_read_b64_tr_b16 v[246:247], v5 offset:15360
	v_add_f32_e32 v2, v99, v2
	v_exp_f32_e32 v101, v101
	v_add_f32_e32 v2, v100, v2
	v_cvt_pk_bf16_f32 v94, v94, v95
	v_add_f32_e32 v2, v101, v2
	s_waitcnt lgkmcnt(6)
	v_mfma_f32_32x32x16_bf16 v[6:21], v[86:89], v[74:77], v[6:21]
	v_cvt_pk_bf16_f32 v95, v96, v97
	v_cvt_pk_bf16_f32 v96, v98, v99
	v_cvt_pk_bf16_f32 v97, v100, v101
	ds_read_b64_tr_b16 v[74:75], v5 offset:13824
	ds_read_b64_tr_b16 v[76:77], v5 offset:15872
	v_permlane32_swap_b32_e32 v94, v96
	v_permlane32_swap_b32_e32 v95, v97
	v_mov_b32_e32 v3, v2
	s_waitcnt lgkmcnt(6)
	s_nop 0
	v_mfma_f32_32x32x16_bf16 v[54:69], v[94:97], v[228:231], v[54:69]
	v_add_u32_e32 v238, 2, v236
	s_waitcnt lgkmcnt(4)
	v_mfma_f32_32x32x16_bf16 v[38:53], v[94:97], v[240:243], v[38:53]
	s_add_i32 m0, s3, 0x10000
	s_add_i32 s100, s100, 1
	s_add_i32 s53, s53, 0x4000
	global_load_lds_dwordx4 v[108:109], off
	s_and_b32 s53, s53, 0xc000
	v_permlane32_swap_b32_e32 v2, v3
	s_waitcnt lgkmcnt(2)
	v_mfma_f32_32x32x16_bf16 v[22:37], v[94:97], v[244:247], v[22:37]
	s_waitcnt lgkmcnt(0)
	v_mfma_f32_32x32x16_bf16 v[6:21], v[94:97], v[74:77], v[6:21]
	s_and_saveexec_b64 s[10:11], vcc
	s_xor_b64 s[10:11], exec, s[10:11]
	v_add_u32_e32 v236, 2, v236
	s_or_saveexec_b64 s[14:15], s[10:11]
	v_add_f32_e32 v2, v2, v3
	v_add_f32_e32 v219, v219, v2
	s_xor_b64 exec, exec, s[14:15]
	s_cbranch_execz .LBB0_936
	s_and_b32 s29, s60, 0xc000
	s_add_i32 s12, s29, 0x8000
	v_add_u32_e32 v2, s12, v207
	s_waitcnt vmcnt(6)
	s_waitcnt lgkmcnt(0)
	s_barrier
	v_add_u32_e32 v3, v2, v167
	ds_read_b128 v[70:73], v3 offset:32768
	v_add_u32_e32 v3, v2, v212
	ds_read_b128 v[90:93], v3 offset:32768
	v_add_u32_e32 v3, v2, v214
	ds_read_b128 v[94:97], v3 offset:32768
	v_add_u32_e32 v3, v2, v216
	ds_read_b128 v[98:101], v3 offset:32768
	v_add_u32_e32 v3, s12, v211
	ds_read_b128 v[86:89], v3 offset:32768
	v_add_u32_e32 v3, s12, v213
	ds_read_b128 v[228:231], v3 offset:32768
	v_add_u32_e32 v3, s12, v215
	ds_read_b128 v[240:243], v3 offset:32768
	v_add_u32_e32 v3, s12, v217
	ds_read_b128 v[244:247], v3 offset:32768
	v_add_u32_e32 v3, 0x7f, v235
	v_cmp_le_i32_e64 s[10:11], s27, v3
	v_cmp_gt_i32_e32 vcc, s27, v3
	v_cmp_ge_i32_e64 s[12:13], s18, v237
	v_cvt_f32_i32_e32 v2, v237
	s_and_b64 s[10:11], s[10:11], s[12:13]
	s_cmp_eq_u64 s[10:11], 0
	s_cbranch_scc0 .Lattn_nl2
	s_waitcnt lgkmcnt(7)
	v_mfma_f32_32x32x16_bf16 v[70:85], v[70:73], v[114:117], 0
	v_cndmask_b32_e64 v3, -v189, v189, vcc
	v_sub_f32_e32 v2, v191, v2
	v_mul_f32_e64 v2, v2, -v3
	v_cvt_pk_bf16_f32 v5, v2, v3
	v_lshlrev_b32_e32 v196, 16, v5
	v_and_b32_e32 v197, 0xffff0000, v5
	s_waitcnt lgkmcnt(6)
	v_mfma_f32_32x32x16_bf16 v[70:85], v[90:93], v[118:121], v[70:85]
	v_pk_add_f32 v[2:3], v[2:3], v[196:197] neg_lo:[0,1] neg_hi:[0,1]
	s_nop 0
	v_cvt_pk_bf16_f32 v2, v2, v3
	v_and_b32_e32 v3, 0xffff, v5
	v_lshl_or_b32 v183, v2, 16, v3
	s_waitcnt lgkmcnt(5)
	v_mfma_f32_32x32x16_bf16 v[70:85], v[94:97], v[122:125], v[70:85]
	v_lshrrev_b32_e32 v3, 16, v5
	v_and_or_b32 v2, v2, s28, v3
	v_cndmask_b32_e64 v3, 0, v2, s[4:5]
	v_cndmask_b32_e64 v2, 0, v183, s[4:5]
	v_mov_b32_e32 v5, v4
	s_waitcnt lgkmcnt(4)
	v_mfma_f32_32x32x16_bf16 v[70:85], v[98:101], v[126:129], v[70:85]
	s_waitcnt lgkmcnt(3)
	v_mfma_f32_32x32x16_bf16 v[86:101], v[86:89], v[114:117], 0
	s_waitcnt lgkmcnt(2)
	v_mfma_f32_32x32x16_bf16 v[86:101], v[228:231], v[118:121], v[86:101]
	s_waitcnt lgkmcnt(1)
	v_mfma_f32_32x32x16_bf16 v[86:101], v[240:243], v[122:125], v[86:101]
	s_waitcnt lgkmcnt(0)
	v_mfma_f32_32x32x16_bf16 v[86:101], v[244:247], v[126:129], v[86:101]
	v_mfma_f32_32x32x16_bf16 v[70:85], v[110:113], v[2:5], v[70:85]
	v_mfma_f32_32x32x16_bf16 v[86:101], v[176:179], v[2:5], v[86:101]
	s_branch .Lattn_exp2
